# v38 + MLP-out main residual loads issued 3 row groups ahead with counted vmcnt + accumulator zeroing with v_mov_b64 pairs (stack of two changes that were each within noise alone)
# speedup vs baseline: 1.0054x; 1.0054x over previous
.LBB0_363:
	s_ashr_i32 s65, s64, 31
	s_lshl_b64 s[24:25], s[64:65], 20
	s_add_u32 s66, s93, s24
	s_addc_u32 s67, s94, s25
	s_and_b64 s[24:25], s[22:23], exec
	s_cselect_b32 s4, s67, s19
	s_cselect_b32 s24, s66, s18
	s_ashr_i32 s63, s62, 31
	s_lshl_b64 s[26:27], s[62:63], 20
	s_add_u32 s68, s95, s26
	s_addc_u32 s69, s38, s27
	s_and_b64 s[22:23], s[22:23], exec
	s_cselect_b32 s25, s69, s21
	s_cselect_b32 s26, s68, s20
	s_add_u32 s18, s18, 0x80080
	s_addc_u32 s19, s19, 0
	s_add_u32 s27, s20, 0x100
	v_mov_b64_e32 v[2:3], 0
	s_addc_u32 s28, s21, 0
	s_mov_b32 s29, -2
	v_mov_b64_e32 v[4:5], 0
	v_mov_b64_e32 v[6:7], 0
	v_mov_b64_e32 v[8:9], 0
	v_mov_b64_e32 v[18:19], 0
	v_mov_b64_e32 v[20:21], 0
	v_mov_b64_e32 v[22:23], 0
	v_mov_b64_e32 v[24:25], 0
	v_mov_b64_e32 v[34:35], 0
	v_mov_b64_e32 v[36:37], 0
	v_mov_b64_e32 v[38:39], 0
	v_mov_b64_e32 v[40:41], 0
	v_mov_b64_e32 v[50:51], 0
	v_mov_b64_e32 v[52:53], 0
	v_mov_b64_e32 v[54:55], 0
	v_mov_b64_e32 v[56:57], 0
	v_mov_b64_e32 v[10:11], 0
	v_mov_b64_e32 v[12:13], 0
	v_mov_b64_e32 v[14:15], 0
	v_mov_b64_e32 v[16:17], 0
	v_mov_b64_e32 v[26:27], 0
	v_mov_b64_e32 v[28:29], 0
	v_mov_b64_e32 v[30:31], 0
	v_mov_b64_e32 v[32:33], 0
	v_mov_b64_e32 v[42:43], 0
	v_mov_b64_e32 v[44:45], 0
	v_mov_b64_e32 v[46:47], 0
	v_mov_b64_e32 v[48:49], 0
	v_mov_b64_e32 v[58:59], 0
	v_mov_b64_e32 v[60:61], 0
	v_mov_b64_e32 v[62:63], 0
	v_mov_b64_e32 v[64:65], 0
	v_mov_b64_e32 v[66:67], 0
	v_mov_b64_e32 v[68:69], 0
	v_mov_b64_e32 v[70:71], 0
	v_mov_b64_e32 v[72:73], 0
	v_mov_b64_e32 v[82:83], 0
	v_mov_b64_e32 v[84:85], 0
	v_mov_b64_e32 v[86:87], 0
	v_mov_b64_e32 v[88:89], 0
	v_mov_b64_e32 v[98:99], 0
	v_mov_b64_e32 v[100:101], 0
	v_mov_b64_e32 v[102:103], 0
	v_mov_b64_e32 v[104:105], 0
	v_mov_b64_e32 v[114:115], 0
	v_mov_b64_e32 v[116:117], 0
	v_mov_b64_e32 v[118:119], 0
	v_mov_b64_e32 v[120:121], 0
	v_mov_b64_e32 v[74:75], 0
	v_mov_b64_e32 v[76:77], 0
	v_mov_b64_e32 v[78:79], 0
	v_mov_b64_e32 v[80:81], 0
	v_mov_b64_e32 v[90:91], 0
	v_mov_b64_e32 v[92:93], 0
	v_mov_b64_e32 v[94:95], 0
	v_mov_b64_e32 v[96:97], 0
	v_mov_b64_e32 v[106:107], 0
	v_mov_b64_e32 v[108:109], 0
	v_mov_b64_e32 v[110:111], 0
	v_mov_b64_e32 v[112:113], 0
	v_mov_b64_e32 v[122:123], 0
	v_mov_b64_e32 v[124:125], 0
	v_mov_b64_e32 v[126:127], 0
	v_mov_b64_e32 v[128:129], 0

.LBB0_985:
	s_lshl_b32 s17, s56, 20
	s_and_b32 s17, s17, 0x700000
	s_add_u32 s20, s37, s17
	s_addc_u32 s21, s46, 0
	s_and_b64 s[26:27], s[26:27], exec
	s_cselect_b32 s17, s21, s23
	s_cselect_b32 s58, s20, s22
	s_add_u32 s59, s24, 0x100
	v_mov_b64_e32 v[2:3], 0
	s_addc_u32 s60, s25, 0
	s_mov_b32 s61, -2
	v_mov_b64_e32 v[4:5], 0
	v_mov_b64_e32 v[6:7], 0
	v_mov_b64_e32 v[8:9], 0
	v_mov_b64_e32 v[10:11], 0
	v_mov_b64_e32 v[12:13], 0
	v_mov_b64_e32 v[18:19], 0
	v_mov_b64_e32 v[20:21], 0
	v_mov_b64_e32 v[26:27], 0
	v_mov_b64_e32 v[28:29], 0
	v_mov_b64_e32 v[34:35], 0
	v_mov_b64_e32 v[36:37], 0
	v_mov_b64_e32 v[42:43], 0
	v_mov_b64_e32 v[44:45], 0
	v_mov_b64_e32 v[50:51], 0
	v_mov_b64_e32 v[52:53], 0
	v_mov_b64_e32 v[14:15], 0
	v_mov_b64_e32 v[16:17], 0
	v_mov_b64_e32 v[22:23], 0
	v_mov_b64_e32 v[24:25], 0
	v_mov_b64_e32 v[30:31], 0
	v_mov_b64_e32 v[32:33], 0
	v_mov_b64_e32 v[38:39], 0
	v_mov_b64_e32 v[40:41], 0
	v_mov_b64_e32 v[46:47], 0
	v_mov_b64_e32 v[48:49], 0
	v_mov_b64_e32 v[54:55], 0
	v_mov_b64_e32 v[56:57], 0
	v_mov_b64_e32 v[58:59], 0
	v_mov_b64_e32 v[60:61], 0
	v_mov_b64_e32 v[62:63], 0
	v_mov_b64_e32 v[64:65], 0
	v_mov_b64_e32 v[66:67], 0
	v_mov_b64_e32 v[68:69], 0
	v_mov_b64_e32 v[70:71], 0
	v_mov_b64_e32 v[72:73], 0
	v_mov_b64_e32 v[74:75], 0
	v_mov_b64_e32 v[76:77], 0
	v_mov_b64_e32 v[82:83], 0
	v_mov_b64_e32 v[84:85], 0
	v_mov_b64_e32 v[90:91], 0
	v_mov_b64_e32 v[92:93], 0
	v_mov_b64_e32 v[98:99], 0
	v_mov_b64_e32 v[100:101], 0
	v_mov_b64_e32 v[106:107], 0
	v_mov_b64_e32 v[108:109], 0
	v_mov_b64_e32 v[114:115], 0
	v_mov_b64_e32 v[116:117], 0
	v_mov_b64_e32 v[78:79], 0
	v_mov_b64_e32 v[80:81], 0
	v_mov_b64_e32 v[86:87], 0
	v_mov_b64_e32 v[88:89], 0
	v_mov_b64_e32 v[94:95], 0
	v_mov_b64_e32 v[96:97], 0
	v_mov_b64_e32 v[102:103], 0
	v_mov_b64_e32 v[104:105], 0
	v_mov_b64_e32 v[110:111], 0
	v_mov_b64_e32 v[112:113], 0
	v_mov_b64_e32 v[118:119], 0
	v_mov_b64_e32 v[120:121], 0
	v_mov_b64_e32 v[122:123], 0
	v_mov_b64_e32 v[124:125], 0
	v_mov_b64_e32 v[126:127], 0
	v_mov_b64_e32 v[128:129], 0

.LBB0_1001:
	v_mov_b64_e32 v[2:3], 0
	s_mov_b32 s21, 0
	s_mov_b64 s[26:27], -1
	s_mov_b64 s[28:29], 0
	v_mov_b64_e32 v[4:5], 0
	v_mov_b64_e32 v[6:7], 0
	v_mov_b64_e32 v[8:9], 0
	v_mov_b64_e32 v[10:11], 0
	v_mov_b64_e32 v[12:13], 0
	v_mov_b64_e32 v[18:19], 0
	v_mov_b64_e32 v[20:21], 0
	v_mov_b64_e32 v[26:27], 0
	v_mov_b64_e32 v[28:29], 0
	v_mov_b64_e32 v[34:35], 0
	v_mov_b64_e32 v[36:37], 0
	v_mov_b64_e32 v[42:43], 0
	v_mov_b64_e32 v[44:45], 0
	v_mov_b64_e32 v[50:51], 0
	v_mov_b64_e32 v[52:53], 0
	v_mov_b64_e32 v[14:15], 0
	v_mov_b64_e32 v[16:17], 0
	v_mov_b64_e32 v[22:23], 0
	v_mov_b64_e32 v[24:25], 0
	v_mov_b64_e32 v[30:31], 0
	v_mov_b64_e32 v[32:33], 0
	v_mov_b64_e32 v[38:39], 0
	v_mov_b64_e32 v[40:41], 0
	v_mov_b64_e32 v[46:47], 0
	v_mov_b64_e32 v[48:49], 0
	v_mov_b64_e32 v[54:55], 0
	v_mov_b64_e32 v[56:57], 0
	v_mov_b64_e32 v[58:59], 0
	v_mov_b64_e32 v[60:61], 0
	v_mov_b64_e32 v[62:63], 0
	v_mov_b64_e32 v[64:65], 0
	v_mov_b64_e32 v[66:67], 0
	v_mov_b64_e32 v[68:69], 0
	v_mov_b64_e32 v[70:71], 0
	v_mov_b64_e32 v[72:73], 0
	v_mov_b64_e32 v[74:75], 0
	v_mov_b64_e32 v[76:77], 0
	v_mov_b64_e32 v[82:83], 0
	v_mov_b64_e32 v[84:85], 0
	v_mov_b64_e32 v[90:91], 0
	v_mov_b64_e32 v[92:93], 0
	v_mov_b64_e32 v[98:99], 0
	v_mov_b64_e32 v[100:101], 0
	v_mov_b64_e32 v[106:107], 0
	v_mov_b64_e32 v[108:109], 0
	v_mov_b64_e32 v[114:115], 0
	v_mov_b64_e32 v[116:117], 0
	v_mov_b64_e32 v[78:79], 0
	v_mov_b64_e32 v[80:81], 0
	v_mov_b64_e32 v[86:87], 0
	v_mov_b64_e32 v[88:89], 0
	v_mov_b64_e32 v[94:95], 0
	v_mov_b64_e32 v[96:97], 0
	v_mov_b64_e32 v[102:103], 0
	v_mov_b64_e32 v[104:105], 0
	v_mov_b64_e32 v[110:111], 0
	v_mov_b64_e32 v[112:113], 0
	v_mov_b64_e32 v[118:119], 0
	v_mov_b64_e32 v[120:121], 0
	v_mov_b64_e32 v[122:123], 0
	v_mov_b64_e32 v[124:125], 0
	v_mov_b64_e32 v[126:127], 0
	v_mov_b64_e32 v[128:129], 0

.LBB0_1271:
	s_ashr_i32 s23, s22, 31
	s_lshl_b64 s[24:25], s[22:23], 20
	s_add_u32 s24, s44, s24
	s_addc_u32 s25, s45, s25
	s_and_b64 s[26:27], s[36:37], exec
	s_cselect_b32 s60, s25, s29
	s_cselect_b32 s61, s24, s28
	s_ashr_i32 s21, s20, 31
	s_lshl_b64 s[26:27], s[20:21], 20
	s_add_u32 s26, s46, s26
	s_addc_u32 s27, s47, s27
	s_and_b64 s[36:37], s[36:37], exec
	s_cselect_b32 s21, s27, s31
	s_cselect_b32 s62, s26, s30
	s_add_u32 s28, s28, 0x80080
	s_addc_u32 s29, s29, 0
	s_add_u32 s63, s30, 0x100
	v_mov_b64_e32 v[2:3], 0
	s_addc_u32 s64, s31, 0
	s_mov_b32 s65, -2
	v_mov_b64_e32 v[4:5], 0
	v_mov_b64_e32 v[6:7], 0
	v_mov_b64_e32 v[8:9], 0
	v_mov_b64_e32 v[18:19], 0
	v_mov_b64_e32 v[20:21], 0
	v_mov_b64_e32 v[22:23], 0
	v_mov_b64_e32 v[24:25], 0
	v_mov_b64_e32 v[34:35], 0
	v_mov_b64_e32 v[36:37], 0
	v_mov_b64_e32 v[38:39], 0
	v_mov_b64_e32 v[40:41], 0
	v_mov_b64_e32 v[50:51], 0
	v_mov_b64_e32 v[52:53], 0
	v_mov_b64_e32 v[54:55], 0
	v_mov_b64_e32 v[56:57], 0
	v_mov_b64_e32 v[10:11], 0
	v_mov_b64_e32 v[12:13], 0
	v_mov_b64_e32 v[14:15], 0
	v_mov_b64_e32 v[16:17], 0
	v_mov_b64_e32 v[26:27], 0
	v_mov_b64_e32 v[28:29], 0
	v_mov_b64_e32 v[30:31], 0
	v_mov_b64_e32 v[32:33], 0
	v_mov_b64_e32 v[42:43], 0
	v_mov_b64_e32 v[44:45], 0
	v_mov_b64_e32 v[46:47], 0
	v_mov_b64_e32 v[48:49], 0
	v_mov_b64_e32 v[58:59], 0
	v_mov_b64_e32 v[60:61], 0
	v_mov_b64_e32 v[62:63], 0
	v_mov_b64_e32 v[64:65], 0
	v_mov_b64_e32 v[66:67], 0
	v_mov_b64_e32 v[68:69], 0
	v_mov_b64_e32 v[70:71], 0
	v_mov_b64_e32 v[72:73], 0
	v_mov_b64_e32 v[82:83], 0
	v_mov_b64_e32 v[84:85], 0
	v_mov_b64_e32 v[86:87], 0
	v_mov_b64_e32 v[88:89], 0
	v_mov_b64_e32 v[98:99], 0
	v_mov_b64_e32 v[100:101], 0
	v_mov_b64_e32 v[102:103], 0
	v_mov_b64_e32 v[104:105], 0
	v_mov_b64_e32 v[130:131], 0
	v_mov_b64_e32 v[132:133], 0
	v_mov_b64_e32 v[134:135], 0
	v_mov_b64_e32 v[136:137], 0
	v_mov_b64_e32 v[74:75], 0
	v_mov_b64_e32 v[76:77], 0
	v_mov_b64_e32 v[78:79], 0
	v_mov_b64_e32 v[80:81], 0
	v_mov_b64_e32 v[90:91], 0
	v_mov_b64_e32 v[92:93], 0
	v_mov_b64_e32 v[94:95], 0
	v_mov_b64_e32 v[96:97], 0
	v_mov_b64_e32 v[106:107], 0
	v_mov_b64_e32 v[108:109], 0
	v_mov_b64_e32 v[110:111], 0
	v_mov_b64_e32 v[112:113], 0
	v_mov_b64_e32 v[138:139], 0
	v_mov_b64_e32 v[140:141], 0
	v_mov_b64_e32 v[142:143], 0
	v_mov_b64_e32 v[144:145], 0
